# persistent GEMM tiles: next tile's first K-tile DMA issued by the non-loader waves (4-7) so loaders go straight to the epilogue
# speedup vs baseline: 1.0102x; 1.0102x over previous
; template <class AL, class BL>
; DEV void gemm_mainloop_p(Acc& acc, const AL& al, const BL& bl, int m0, int n0, int m0n, int n0n, int K, char* lds,
;                          GemmPipe& gp) {
;   const int tid = tidx_full();
;   const int wave = tid >> 6, lane = tid & 63;
;   const int wm = (wave >> 2) * 128, wn = (wave & 3) * 64;
;   const int lr = lane & 31, lh = lane >> 5;
;   const int nk = K / BK;
;   if (!gp.primed) {
;     gp.ra = al.load(tid, m0, 0);
;     gp.rb = bl.load(tid, n0, 0);
;     __syncthreads();
;     al.store(tid, lds, gp.ra);
;     bl.store(tid, lds + TILE_BYTES, gp.rb);
;     gp.ra = al.load(tid, m0, BK);
;     gp.rb = bl.load(tid, n0, BK);
;     __syncthreads();
;   }
; DEV void phase_p1(const Params& p, int g, char* smem) {
;     ...
;     for (int iter = 0;; ++iter) {
;       int mt, nt, mtn, ntn;
;       if (!tile_map(iter, 128, 18, mt, nt)) break;
;       const bool more = tile_map(iter + 1, 128, 18, mtn, ntn);
;       if (!more) { mtn = mt; ntn = nt; }
;       Acc acc;
;       acc_zero(acc);
;       const int m0 = mt * 256, n0 = nt * 256;
;       RowLoader al{H, 1024}, bl{WinT + (size_t)1536 * 1024, 1024};
;       gemm_mainloop_p(acc, al, bl, m0, n0, mtn * 256, ntn * 256, 1024, smem, gp);
.LBB0_278:
	s_and_b64 vcc, exec, s[2:3]
	s_lshl_b32 s5, s7, 8
	s_lshl_b32 s4, s8, 8
	v_lshrrev_b32_e32 v149, 6, v202
	v_and_b32_e32 v148, 63, v202
	s_nop 0
	v_readfirstlane_b32 s13, v149
	v_lshrrev_b32_e32 v150, 3, v148
	v_and_b32_e32 v151, 3, v149
	v_lshl_add_u32 v150, v151, 5, v150
	v_and_b32_e32 v151, 7, v148
	v_lshrrev_b32_e32 v128, 4, v148
	v_xor_b32_e32 v151, v128, v151
	v_lshlrev_b32_e32 v151, 4, v151
	s_lshl_b32 s13, s13, 12
	v_add_u32_e32 v128, s5, v150
	v_lshlrev_b32_e32 v128, 11, v128
	v_add_u32_e32 v128, v128, v151
	v_add_u32_e32 v129, 0x3c00, v128
	v_add_u32_e32 v130, 0x7800, v128
	v_add_u32_e32 v131, 0xb400, v128
	v_xor_b32_e32 v129, 0x40, v129
	v_xor_b32_e32 v131, 0x40, v131
	v_add_u32_e32 v132, s4, v150
	v_lshlrev_b32_e32 v132, 11, v132
	v_add_u32_e32 v132, v132, v151
	v_add_u32_e32 v133, 0x3c00, v132
	v_add_u32_e32 v134, 0x7800, v132
	v_add_u32_e32 v135, 0xb400, v132
	v_xor_b32_e32 v133, 0x40, v133
	v_xor_b32_e32 v135, 0x40, v135
	v_add_u32_e32 v136, 0x40000, v128
	v_add_u32_e32 v137, 0x40000, v129
	v_add_u32_e32 v138, 0x40000, v130
	v_add_u32_e32 v139, 0x40000, v131
	v_add_u32_e32 v140, 0x40000, v132
	v_add_u32_e32 v141, 0x40000, v133
	v_add_u32_e32 v142, 0x40000, v134
	v_add_u32_e32 v143, 0x40000, v135
	v_lshrrev_b32_e32 v161, 6, v202
	v_and_b32_e32 v160, 63, v202
	v_bfe_u32 v242, v160, 1, 3
	v_lshrrev_b32_e32 v243, 4, v160
	v_xor_b32_e32 v242, v242, v243
	v_lshlrev_b32_e32 v242, 4, v242
	v_and_b32_e32 v243, 15, v160
	v_lshlrev_b32_e32 v243, 7, v243
	v_lshrrev_b32_e32 v144, 2, v161
	v_lshl_add_u32 v144, v144, 14, v243
	v_and_b32_e32 v146, 3, v161
	v_lshl_add_u32 v146, v146, 13, v243
	v_add_u32_e32 v146, 0x10000, v146
	v_xor_b32_e32 v145, 0x40, v242
	v_add_u32_e32 v145, v144, v145
	v_add_u32_e32 v144, v144, v242
	v_xor_b32_e32 v147, 0x40, v242
	v_add_u32_e32 v147, v146, v147
	v_add_u32_e32 v146, v146, v242
	s_mov_b64 s[14:15], s[64:65]
	s_mov_b64 s[16:17], s[24:25]
	s_cbranch_vccnz .Lp1a_primed
	s_cmp_lt_u32 s13, 0x4000
	s_cbranch_scc0 .Lp1a_d1
	s_add_u32 m0, s13, 0x0
	s_nop 0
	global_load_lds_dwordx4 v128, s[14:15]
	global_load_lds_dwordx4 v129, s[14:15] offset:1024
	global_load_lds_dwordx4 v130, s[14:15] offset:2048
	global_load_lds_dwordx4 v131, s[14:15] offset:3072
	s_add_u32 m0, s13, 0x10000
	s_nop 0
	global_load_lds_dwordx4 v132, s[16:17]
	global_load_lds_dwordx4 v133, s[16:17] offset:1024
	global_load_lds_dwordx4 v134, s[16:17] offset:2048
	global_load_lds_dwordx4 v135, s[16:17] offset:3072
	s_add_u32 m0, s13, 0x4000
	s_nop 0
	global_load_lds_dwordx4 v136, s[14:15]
	global_load_lds_dwordx4 v137, s[14:15] offset:1024
	global_load_lds_dwordx4 v138, s[14:15] offset:2048
	global_load_lds_dwordx4 v139, s[14:15] offset:3072
	s_add_u32 m0, s13, 0x14000
	s_nop 0
	global_load_lds_dwordx4 v140, s[16:17]
	global_load_lds_dwordx4 v141, s[16:17] offset:1024
	global_load_lds_dwordx4 v142, s[16:17] offset:2048
	global_load_lds_dwordx4 v143, s[16:17] offset:3072

; template <class AL, class BL>
; DEV void gemm_mainloop_p(Acc& acc, const AL& al, const BL& bl, int m0, int n0, int m0n, int n0n, int K, char* lds,
;                          GemmPipe& gp) {
;   const int tid = tidx_full();
;   const int wave = tid >> 6, lane = tid & 63;
;   const int wm = (wave >> 2) * 128, wn = (wave & 3) * 64;
;   const int lr = lane & 31, lh = lane >> 5;
;   const int nk = K / BK;
;   if (!gp.primed) {
;     gp.ra = al.load(tid, m0, 0);
;     gp.rb = bl.load(tid, n0, 0);
;     __syncthreads();
;     al.store(tid, lds, gp.ra);
;     bl.store(tid, lds + TILE_BYTES, gp.rb);
;     gp.ra = al.load(tid, m0, BK);
;     gp.rb = bl.load(tid, n0, BK);
;     __syncthreads();
;   }
; DEV void phase_p1(const Params& p, int g, char* smem) {
;     ...
;     for (int iter = 0;; ++iter) {
;       int cm, tn, cmn, tnn;
;       if (!tile_map(iter, 6, 128, cm, tn)) break;
;       const bool more = tile_map(iter + 1, 6, 128, cmn, tnn);
;       if (!more) { cmn = cm; tnn = tn; }
;       Acc acc;
;       acc_zero(acc);
;       const int m0 = cm * 256, n0 = tn * 256;
;       RowLoader al{WinT, 1024}, bl{H, 1024};
;       gemm_mainloop_p(acc, al, bl, m0, n0, cmn * 256, tnn * 256, 1024, smem, gp);
.LBB0_560:
	s_and_b64 vcc, exec, s[2:3]
	s_lshl_b32 s11, s7, 8
	s_lshl_b32 s2, s8, 8
	v_lshrrev_b32_e32 v149, 6, v202
	v_and_b32_e32 v148, 63, v202
	s_nop 0
	v_readfirstlane_b32 s9, v149
	v_lshrrev_b32_e32 v150, 3, v148
	v_and_b32_e32 v151, 3, v149
	v_lshl_add_u32 v150, v151, 5, v150
	v_and_b32_e32 v151, 7, v148
	v_lshrrev_b32_e32 v128, 4, v148
	v_xor_b32_e32 v151, v128, v151
	v_lshlrev_b32_e32 v151, 4, v151
	s_lshl_b32 s9, s9, 12
	v_add_u32_e32 v128, s11, v150
	v_lshlrev_b32_e32 v128, 11, v128
	v_add_u32_e32 v128, v128, v151
	v_add_u32_e32 v129, 0x3c00, v128
	v_add_u32_e32 v130, 0x7800, v128
	v_add_u32_e32 v131, 0xb400, v128
	v_xor_b32_e32 v129, 0x40, v129
	v_xor_b32_e32 v131, 0x40, v131
	v_add_u32_e32 v132, s2, v150
	v_lshlrev_b32_e32 v132, 11, v132
	v_add_u32_e32 v132, v132, v151
	v_add_u32_e32 v133, 0x3c00, v132
	v_add_u32_e32 v134, 0x7800, v132
	v_add_u32_e32 v135, 0xb400, v132
	v_xor_b32_e32 v133, 0x40, v133
	v_xor_b32_e32 v135, 0x40, v135
	v_add_u32_e32 v136, 0x40000, v128
	v_add_u32_e32 v137, 0x40000, v129
	v_add_u32_e32 v138, 0x40000, v130
	v_add_u32_e32 v139, 0x40000, v131
	v_add_u32_e32 v140, 0x40000, v132
	v_add_u32_e32 v141, 0x40000, v133
	v_add_u32_e32 v142, 0x40000, v134
	v_add_u32_e32 v143, 0x40000, v135
	v_lshrrev_b32_e32 v161, 6, v202
	v_and_b32_e32 v160, 63, v202
	v_bfe_u32 v242, v160, 1, 3
	v_lshrrev_b32_e32 v243, 4, v160
	v_xor_b32_e32 v242, v242, v243
	v_lshlrev_b32_e32 v242, 4, v242
	v_and_b32_e32 v243, 15, v160
	v_lshlrev_b32_e32 v243, 7, v243
	v_lshrrev_b32_e32 v144, 2, v161
	v_lshl_add_u32 v144, v144, 14, v243
	v_and_b32_e32 v146, 3, v161
	v_lshl_add_u32 v146, v146, 13, v243
	v_add_u32_e32 v146, 0x10000, v146
	v_xor_b32_e32 v145, 0x40, v242
	v_add_u32_e32 v145, v144, v145
	v_add_u32_e32 v144, v144, v242
	v_xor_b32_e32 v147, 0x40, v242
	v_add_u32_e32 v147, v146, v147
	v_add_u32_e32 v146, v146, v242
	s_mov_b64 s[14:15], s[88:89]
	s_mov_b64 s[16:17], s[64:65]
	s_cbranch_vccnz .Lp1b_primed
	s_cmp_lt_u32 s9, 0x4000
	s_cbranch_scc0 .Lp1b_d1
	s_add_u32 m0, s9, 0x0
	s_nop 0
	global_load_lds_dwordx4 v128, s[14:15]
	global_load_lds_dwordx4 v129, s[14:15] offset:1024
	global_load_lds_dwordx4 v130, s[14:15] offset:2048
	global_load_lds_dwordx4 v131, s[14:15] offset:3072
	s_add_u32 m0, s9, 0x10000
	s_nop 0
	global_load_lds_dwordx4 v132, s[16:17]
	global_load_lds_dwordx4 v133, s[16:17] offset:1024
	global_load_lds_dwordx4 v134, s[16:17] offset:2048
	global_load_lds_dwordx4 v135, s[16:17] offset:3072
	s_add_u32 m0, s9, 0x4000
	s_nop 0
	global_load_lds_dwordx4 v136, s[14:15]
	global_load_lds_dwordx4 v137, s[14:15] offset:1024
	global_load_lds_dwordx4 v138, s[14:15] offset:2048
	global_load_lds_dwordx4 v139, s[14:15] offset:3072
	s_add_u32 m0, s9, 0x14000
	s_nop 0
	global_load_lds_dwordx4 v140, s[16:17]
	global_load_lds_dwordx4 v141, s[16:17] offset:1024
	global_load_lds_dwordx4 v142, s[16:17] offset:2048
	global_load_lds_dwordx4 v143, s[16:17] offset:3072

; template <class AL, class BL>
; DEV void gemm_mainloop(Acc& acc, const AL& al, const BL& bl, int m0, int n0, int kbeg, int kend, char* lds) {
;   const int tid = tidx_full();
;   const int wave = tid >> 6, lane = tid & 63;
;   const int wm = (wave >> 2) * 128, wn = (wave & 3) * 64;
;   const int lr = lane & 31, lh = lane >> 5;
;   const int nk = (kend - kbeg) / BK;
;   R4 a0 = al.load(tid, m0, kbeg);
;   R4 b0 = bl.load(tid, n0, kbeg);
;   __syncthreads();
;   al.store(tid, lds, a0);
;   bl.store(tid, lds + TILE_BYTES, b0);
;   a0 = al.load(tid, m0, kbeg + BK);
;   b0 = bl.load(tid, n0, kbeg + BK);
;   __syncthreads();
; DEV void phase_p3b(const Params& p, int g, char* smem) {
;     ...
;   for (int iter = 0;; ++iter) {
;     int mt, nt;
;     if (!tile_map(iter, 128, 4, mt, nt)) break;
;     const int m0 = mt * 256, n0 = nt * 256;
;     Acc acc;
;     acc_zero(acc);
;     RowLoader al{PHG + 1024, 2560}, bl{WoutT, 1024};
;     gemm_mainloop(acc, al, bl, m0, n0, 0, 1024, smem);
.LBB0_1001:
	v_readlane_b32 s2, v251, 23
	v_readlane_b32 s3, v251, 24
	v_readlane_b32 s10, v251, 21
	v_readlane_b32 s11, v251, 22
	s_lshl_b32 s5, s7, 8
	s_lshl_b32 s4, s8, 8
	v_lshrrev_b32_e32 v149, 6, v202
	v_and_b32_e32 v148, 63, v202
	s_nop 0
	v_readfirstlane_b32 s9, v149
	v_lshrrev_b32_e32 v150, 3, v148
	v_and_b32_e32 v151, 3, v149
	v_lshl_add_u32 v150, v151, 5, v150
	v_and_b32_e32 v151, 7, v148
	v_lshrrev_b32_e32 v128, 4, v148
	v_xor_b32_e32 v151, v128, v151
	v_lshlrev_b32_e32 v151, 4, v151
	s_lshl_b32 s9, s9, 12
	v_add_u32_e32 v128, s5, v150
	v_mul_u32_u24_e32 v128, 0x1400, v128
	v_add_u32_e32 v128, v128, v151
	v_add_u32_e32 v129, 0x9c00, v128
	v_add_u32_e32 v130, 0x13800, v128
	v_add_u32_e32 v131, 0x1d400, v128
	v_xor_b32_e32 v129, 0x40, v129
	v_xor_b32_e32 v131, 0x40, v131
	v_add_u32_e32 v136, 0xa0000, v128
	v_add_u32_e32 v137, 0xa0000, v129
	v_add_u32_e32 v138, 0xa0000, v130
	v_add_u32_e32 v139, 0xa0000, v131
	v_add_u32_e32 v132, s4, v150
	v_lshlrev_b32_e32 v132, 11, v132
	v_add_u32_e32 v132, v132, v151
	v_add_u32_e32 v133, 0x3c00, v132
	v_add_u32_e32 v134, 0x7800, v132
	v_add_u32_e32 v135, 0xb400, v132
	v_xor_b32_e32 v133, 0x40, v133
	v_xor_b32_e32 v135, 0x40, v135
	v_add_u32_e32 v140, 0x40000, v132
	v_add_u32_e32 v141, 0x40000, v133
	v_add_u32_e32 v142, 0x40000, v134
	v_add_u32_e32 v143, 0x40000, v135
	v_lshrrev_b32_e32 v161, 6, v202
	v_and_b32_e32 v160, 63, v202
	v_bfe_u32 v164, v160, 1, 3
	v_lshrrev_b32_e32 v199, 4, v160
	v_xor_b32_e32 v164, v164, v199
	v_lshlrev_b32_e32 v164, 4, v164
	v_and_b32_e32 v199, 15, v160
	v_lshlrev_b32_e32 v199, 7, v199
	v_lshrrev_b32_e32 v144, 2, v161
	v_lshl_add_u32 v144, v144, 14, v199
	v_and_b32_e32 v146, 3, v161
	v_lshl_add_u32 v146, v146, 13, v199
	v_add_u32_e32 v146, 0x10000, v146
	v_xor_b32_e32 v145, 0x40, v164
	v_add_u32_e32 v145, v144, v145
	v_add_u32_e32 v144, v144, v164
	v_xor_b32_e32 v147, 0x40, v164
	v_add_u32_e32 v147, v146, v147
	v_add_u32_e32 v146, v146, v164
	s_mov_b64 s[12:13], s[2:3]
	s_mov_b64 s[14:15], s[10:11]
	s_cmp_lt_u32 s9, 0x4000
	s_cbranch_scc0 .Lp3b_d1
	s_add_u32 m0, s9, 0x0
	s_nop 0
	global_load_lds_dwordx4 v128, s[12:13]
	global_load_lds_dwordx4 v129, s[12:13] offset:1024
	global_load_lds_dwordx4 v130, s[12:13] offset:2048
	global_load_lds_dwordx4 v131, s[12:13] offset:3072
	s_add_u32 m0, s9, 0x10000
	s_nop 0
	global_load_lds_dwordx4 v132, s[14:15]
	global_load_lds_dwordx4 v133, s[14:15] offset:1024
	global_load_lds_dwordx4 v134, s[14:15] offset:2048
	global_load_lds_dwordx4 v135, s[14:15] offset:3072
	s_add_u32 m0, s9, 0x4000
	s_nop 0
	global_load_lds_dwordx4 v136, s[12:13]
	global_load_lds_dwordx4 v137, s[12:13] offset:1024
	global_load_lds_dwordx4 v138, s[12:13] offset:2048
	global_load_lds_dwordx4 v139, s[12:13] offset:3072
	s_add_u32 m0, s9, 0x14000
	s_nop 0
	global_load_lds_dwordx4 v140, s[14:15]
	global_load_lds_dwordx4 v141, s[14:15] offset:1024
	global_load_lds_dwordx4 v142, s[14:15] offset:2048
	global_load_lds_dwordx4 v143, s[14:15] offset:3072

; template <class AL, class BL>
; DEV void gemm_mainloop_p(Acc& acc, const AL& al, const BL& bl, int m0, int n0, int m0n, int n0n, int K, char* lds,
;                          GemmPipe& gp) {
;   const int tid = tidx_full();
;   const int wave = tid >> 6, lane = tid & 63;
;   const int wm = (wave >> 2) * 128, wn = (wave & 3) * 64;
;   const int lr = lane & 31, lh = lane >> 5;
;   const int nk = K / BK;
;   if (!gp.primed) {
;     gp.ra = al.load(tid, m0, 0);
;     gp.rb = bl.load(tid, n0, 0);
;     __syncthreads();
;     al.store(tid, lds, gp.ra);
;     bl.store(tid, lds + TILE_BYTES, gp.rb);
;     gp.ra = al.load(tid, m0, BK);
;     gp.rb = bl.load(tid, n0, BK);
;     __syncthreads();
;   }
; DEV void phase_ff1(const Params& p, int g, char* smem) {
;     ...
;   for (int iter = 0;; ++iter) {
;     int mt, nt, mtn, ntn;
;     if (!tile_map(iter, 128, 16, mt, nt)) break;
;     const bool more = tile_map(iter + 1, 128, 16, mtn, ntn);
;     if (!more) { mtn = mt; ntn = nt; }
;     const int m0 = mt * 256, n0 = nt * 256;
;     Acc acc;
;     acc_zero(acc);
;     RowLoader al{H2, 1024}, bl{W, 1024};
;     gemm_mainloop_p(acc, al, bl, m0, n0, mtn * 256, ntn * 256, 1024, smem, gp);
.LBB0_1126:
	v_readlane_b32 s18, v249, 48
	v_readlane_b32 s19, v249, 49
	v_readlane_b32 s20, v251, 25
	v_readlane_b32 s21, v251, 26
	s_and_b64 vcc, exec, s[2:3]
	s_lshl_b32 s5, s9, 8
	s_lshl_b32 s4, s10, 8
	v_lshrrev_b32_e32 v149, 6, v202
	v_and_b32_e32 v148, 63, v202
	s_nop 0
	v_readfirstlane_b32 s13, v149
	v_lshrrev_b32_e32 v150, 3, v148
	v_and_b32_e32 v151, 3, v149
	v_lshl_add_u32 v150, v151, 5, v150
	v_and_b32_e32 v151, 7, v148
	v_lshrrev_b32_e32 v128, 4, v148
	v_xor_b32_e32 v151, v128, v151
	v_lshlrev_b32_e32 v151, 4, v151
	s_lshl_b32 s13, s13, 12
	v_add_u32_e32 v128, s5, v150
	v_lshlrev_b32_e32 v128, 11, v128
	v_add_u32_e32 v128, v128, v151
	v_add_u32_e32 v129, 0x3c00, v128
	v_add_u32_e32 v130, 0x7800, v128
	v_add_u32_e32 v131, 0xb400, v128
	v_xor_b32_e32 v129, 0x40, v129
	v_xor_b32_e32 v131, 0x40, v131
	v_add_u32_e32 v132, s4, v150
	v_lshlrev_b32_e32 v132, 11, v132
	v_add_u32_e32 v132, v132, v151
	v_add_u32_e32 v133, 0x3c00, v132
	v_add_u32_e32 v134, 0x7800, v132
	v_add_u32_e32 v135, 0xb400, v132
	v_xor_b32_e32 v133, 0x40, v133
	v_xor_b32_e32 v135, 0x40, v135
	v_add_u32_e32 v136, 0x40000, v128
	v_add_u32_e32 v137, 0x40000, v129
	v_add_u32_e32 v138, 0x40000, v130
	v_add_u32_e32 v139, 0x40000, v131
	v_add_u32_e32 v140, 0x40000, v132
	v_add_u32_e32 v141, 0x40000, v133
	v_add_u32_e32 v142, 0x40000, v134
	v_add_u32_e32 v143, 0x40000, v135
	v_lshrrev_b32_e32 v161, 6, v202
	v_and_b32_e32 v160, 63, v202
	v_bfe_u32 v242, v160, 1, 3
	v_lshrrev_b32_e32 v243, 4, v160
	v_xor_b32_e32 v242, v242, v243
	v_lshlrev_b32_e32 v242, 4, v242
	v_and_b32_e32 v243, 15, v160
	v_lshlrev_b32_e32 v243, 7, v243
	v_lshrrev_b32_e32 v144, 2, v161
	v_lshl_add_u32 v144, v144, 14, v243
	v_and_b32_e32 v146, 3, v161
	v_lshl_add_u32 v146, v146, 13, v243
	v_add_u32_e32 v146, 0x10000, v146
	v_xor_b32_e32 v145, 0x40, v242
	v_add_u32_e32 v145, v144, v145
	v_add_u32_e32 v144, v144, v242
	v_xor_b32_e32 v147, 0x40, v242
	v_add_u32_e32 v147, v146, v147
	v_add_u32_e32 v146, v146, v242
	s_mov_b64 s[22:23], s[18:19]
	s_mov_b64 s[14:15], s[20:21]
	s_cbranch_vccnz .Lff1_primed
	s_cmp_lt_u32 s13, 0x4000
	s_cbranch_scc0 .Lff1_d1
	s_add_u32 m0, s13, 0x0
	s_nop 0
	global_load_lds_dwordx4 v128, s[22:23]
	global_load_lds_dwordx4 v129, s[22:23] offset:1024
	global_load_lds_dwordx4 v130, s[22:23] offset:2048
	global_load_lds_dwordx4 v131, s[22:23] offset:3072
	s_add_u32 m0, s13, 0x10000
	s_nop 0
	global_load_lds_dwordx4 v132, s[14:15]
	global_load_lds_dwordx4 v133, s[14:15] offset:1024
	global_load_lds_dwordx4 v134, s[14:15] offset:2048
	global_load_lds_dwordx4 v135, s[14:15] offset:3072
	s_add_u32 m0, s13, 0x4000
	s_nop 0
	global_load_lds_dwordx4 v136, s[22:23]
	global_load_lds_dwordx4 v137, s[22:23] offset:1024
	global_load_lds_dwordx4 v138, s[22:23] offset:2048
	global_load_lds_dwordx4 v139, s[22:23] offset:3072
	s_add_u32 m0, s13, 0x14000
	s_nop 0
	global_load_lds_dwordx4 v140, s[14:15]
	global_load_lds_dwordx4 v141, s[14:15] offset:1024
	global_load_lds_dwordx4 v142, s[14:15] offset:2048
	global_load_lds_dwordx4 v143, s[14:15] offset:3072

; template <class AL, class BL>
; DEV void gemm_mainloop(Acc& acc, const AL& al, const BL& bl, int m0, int n0, int kbeg, int kend, char* lds) {
;   const int tid = tidx_full();
;   const int wave = tid >> 6, lane = tid & 63;
;   const int wm = (wave >> 2) * 128, wn = (wave & 3) * 64;
;   const int lr = lane & 31, lh = lane >> 5;
;   const int nk = (kend - kbeg) / BK;
;   R4 a0 = al.load(tid, m0, kbeg);
;   R4 b0 = bl.load(tid, n0, kbeg);
;   __syncthreads();
;   al.store(tid, lds, a0);
;   bl.store(tid, lds + TILE_BYTES, b0);
;   a0 = al.load(tid, m0, kbeg + BK);
;   b0 = bl.load(tid, n0, kbeg + BK);
;   __syncthreads();
; DEV void phase_ff2(const Params& p, int g, char* smem) {
;     ...
;     const int m0 = mt * 256, n0 = nt * 256;
;     Acc acc;
;     acc_zero(acc);
;     RowLoader al{AB, 4096}, bl{W, 4096};
;     gemm_mainloop(acc, al, bl, m0, n0, 0, 4096, smem);
.LBB0_1192:
	s_lshl_b32 s3, s5, 8
	s_lshl_b32 s2, s6, 8
	v_readlane_b32 s0, v251, 30
	v_readlane_b32 s1, v251, 31
	s_mov_b64 s[6:7], s[74:75]
	v_lshrrev_b32_e32 v149, 6, v202
	v_and_b32_e32 v148, 63, v202
	s_nop 0
	v_readfirstlane_b32 s8, v149
	v_lshrrev_b32_e32 v150, 3, v148
	v_and_b32_e32 v151, 3, v149
	v_lshl_add_u32 v150, v151, 5, v150
	v_and_b32_e32 v151, 7, v148
	v_lshrrev_b32_e32 v128, 4, v148
	v_xor_b32_e32 v151, v128, v151
	v_lshlrev_b32_e32 v151, 4, v151
	s_lshl_b32 s8, s8, 12
	v_add_u32_e32 v128, s3, v150
	v_lshlrev_b32_e32 v128, 13, v128
	v_add_u32_e32 v128, v128, v151
	v_add_u32_e32 v129, 0xfc00, v128
	v_add_u32_e32 v130, 0x1f800, v128
	v_add_u32_e32 v131, 0x2f400, v128
	v_xor_b32_e32 v129, 0x40, v129
	v_xor_b32_e32 v131, 0x40, v131
	v_add_u32_e32 v132, s2, v150
	v_lshlrev_b32_e32 v132, 13, v132
	v_add_u32_e32 v132, v132, v151
	v_add_u32_e32 v133, 0xfc00, v132
	v_add_u32_e32 v134, 0x1f800, v132
	v_add_u32_e32 v135, 0x2f400, v132
	v_xor_b32_e32 v133, 0x40, v133
	v_xor_b32_e32 v135, 0x40, v135
	v_lshrrev_b32_e32 v150, 1, v148
	v_and_b32_e32 v150, 7, v150
	v_lshrrev_b32_e32 v151, 5, v148
	v_xor_b32_e32 v150, v150, v151
	v_lshlrev_b32_e32 v150, 4, v150
	v_and_b32_e32 v151, 31, v148
	v_lshlrev_b32_e32 v151, 7, v151
	v_lshrrev_b32_e32 v156, 2, v149
	v_lshl_add_u32 v156, v156, 14, v151
	v_and_b32_e32 v207, 3, v149
	v_lshl_add_u32 v207, v207, 13, v151
	v_add_u32_e32 v207, 0x10000, v207
	v_xor_b32_e32 v159, 0x60, v150
	v_add_u32_e32 v159, v156, v159
	v_xor_b32_e32 v158, 0x40, v150
	v_add_u32_e32 v158, v156, v158
	v_xor_b32_e32 v157, 0x20, v150
	v_add_u32_e32 v157, v156, v157
	v_add_u32_e32 v156, v156, v150
	v_xor_b32_e32 v210, 0x60, v150
	v_add_u32_e32 v210, v207, v210
	v_xor_b32_e32 v209, 0x40, v150
	v_add_u32_e32 v209, v207, v209
	v_xor_b32_e32 v208, 0x20, v150
	v_add_u32_e32 v208, v207, v208
	v_add_u32_e32 v207, v207, v150
	v_add_u32_e32 v136, 0x100000, v128
	v_add_u32_e32 v137, 0x100000, v129
	v_add_u32_e32 v138, 0x100000, v130
	v_add_u32_e32 v139, 0x100000, v131
	v_add_u32_e32 v140, 0x100000, v132
	v_add_u32_e32 v141, 0x100000, v133
	v_add_u32_e32 v142, 0x100000, v134
	v_add_u32_e32 v143, 0x100000, v135
	v_lshrrev_b32_e32 v149, 6, v202
	v_and_b32_e32 v148, 63, v202
	v_bfe_u32 v150, v148, 1, 3
	v_lshrrev_b32_e32 v151, 4, v148
	v_xor_b32_e32 v150, v150, v151
	v_lshlrev_b32_e32 v150, 4, v150
	v_and_b32_e32 v151, 15, v148
	v_lshlrev_b32_e32 v151, 7, v151
	v_lshrrev_b32_e32 v144, 2, v149
	v_lshl_add_u32 v144, v144, 14, v151
	v_and_b32_e32 v146, 3, v149
	v_lshl_add_u32 v146, v146, 13, v151
	v_add_u32_e32 v146, 0x10000, v146
	v_xor_b32_e32 v145, 0x40, v150
	v_add_u32_e32 v145, v144, v145
	v_add_u32_e32 v144, v144, v150
	v_xor_b32_e32 v147, 0x40, v150
	v_add_u32_e32 v147, v146, v147
	v_add_u32_e32 v146, v146, v150
	v_mov_b32_e32 v0, 0
	v_mov_b32_e32 v1, 0
	v_mov_b64_e32 v[2:3], v[0:1]
	v_mov_b64_e32 v[4:5], v[0:1]
	v_mov_b64_e32 v[6:7], v[0:1]
	v_mov_b64_e32 v[8:9], v[0:1]
	v_mov_b64_e32 v[10:11], v[0:1]
	v_mov_b64_e32 v[12:13], v[0:1]
	v_mov_b64_e32 v[14:15], v[0:1]
	v_mov_b64_e32 v[16:17], v[0:1]
	v_mov_b64_e32 v[18:19], v[0:1]
	v_mov_b64_e32 v[20:21], v[0:1]
	v_mov_b64_e32 v[22:23], v[0:1]
	v_mov_b64_e32 v[24:25], v[0:1]
	v_mov_b64_e32 v[26:27], v[0:1]
	v_mov_b64_e32 v[28:29], v[0:1]
	v_mov_b64_e32 v[30:31], v[0:1]
	v_mov_b64_e32 v[32:33], v[0:1]
	v_mov_b64_e32 v[34:35], v[0:1]
	v_mov_b64_e32 v[36:37], v[0:1]
	v_mov_b64_e32 v[38:39], v[0:1]
	v_mov_b64_e32 v[40:41], v[0:1]
	v_mov_b64_e32 v[42:43], v[0:1]
	v_mov_b64_e32 v[44:45], v[0:1]
	v_mov_b64_e32 v[46:47], v[0:1]
	v_mov_b64_e32 v[48:49], v[0:1]
	v_mov_b64_e32 v[50:51], v[0:1]
	v_mov_b64_e32 v[52:53], v[0:1]
	v_mov_b64_e32 v[54:55], v[0:1]
	v_mov_b64_e32 v[56:57], v[0:1]
	v_mov_b64_e32 v[58:59], v[0:1]
	v_mov_b64_e32 v[60:61], v[0:1]
	v_mov_b64_e32 v[62:63], v[0:1]
	v_mov_b64_e32 v[64:65], v[0:1]
	v_mov_b64_e32 v[66:67], v[0:1]
	v_mov_b64_e32 v[68:69], v[0:1]
	v_mov_b64_e32 v[70:71], v[0:1]
	v_mov_b64_e32 v[72:73], v[0:1]
	v_mov_b64_e32 v[74:75], v[0:1]
	v_mov_b64_e32 v[76:77], v[0:1]
	v_mov_b64_e32 v[78:79], v[0:1]
	v_mov_b64_e32 v[80:81], v[0:1]
	v_mov_b64_e32 v[82:83], v[0:1]
	v_mov_b64_e32 v[84:85], v[0:1]
	v_mov_b64_e32 v[86:87], v[0:1]
	v_mov_b64_e32 v[88:89], v[0:1]
	v_mov_b64_e32 v[90:91], v[0:1]
	v_mov_b64_e32 v[92:93], v[0:1]
	v_mov_b64_e32 v[94:95], v[0:1]
	v_mov_b64_e32 v[96:97], v[0:1]
	v_mov_b64_e32 v[98:99], v[0:1]
	v_mov_b64_e32 v[100:101], v[0:1]
	v_mov_b64_e32 v[102:103], v[0:1]
	v_mov_b64_e32 v[104:105], v[0:1]
	v_mov_b64_e32 v[106:107], v[0:1]
	v_mov_b64_e32 v[108:109], v[0:1]
	v_mov_b64_e32 v[110:111], v[0:1]
	v_mov_b64_e32 v[112:113], v[0:1]
	v_mov_b64_e32 v[114:115], v[0:1]
	v_mov_b64_e32 v[116:117], v[0:1]
	v_mov_b64_e32 v[118:119], v[0:1]
	v_mov_b64_e32 v[120:121], v[0:1]
	v_mov_b64_e32 v[122:123], v[0:1]
	v_mov_b64_e32 v[124:125], v[0:1]
	v_mov_b64_e32 v[126:127], v[0:1]
	s_cmp_lt_u32 s8, 0x4000
	s_cbranch_scc0 .Lff2_d1
	s_add_u32 m0, s8, 0x0
	s_nop 0
	global_load_lds_dwordx4 v128, s[6:7]
	global_load_lds_dwordx4 v129, s[6:7] offset:1024
	global_load_lds_dwordx4 v130, s[6:7] offset:2048
	global_load_lds_dwordx4 v131, s[6:7] offset:3072
	s_add_u32 m0, s8, 0x10000
	s_nop 0
	global_load_lds_dwordx4 v132, s[0:1]
	global_load_lds_dwordx4 v133, s[0:1] offset:1024
	global_load_lds_dwordx4 v134, s[0:1] offset:2048
	global_load_lds_dwordx4 v135, s[0:1] offset:3072
	s_add_u32 m0, s8, 0x4000
	s_nop 0
	global_load_lds_dwordx4 v136, s[6:7]
	global_load_lds_dwordx4 v137, s[6:7] offset:1024
	global_load_lds_dwordx4 v138, s[6:7] offset:2048
	global_load_lds_dwordx4 v139, s[6:7] offset:3072
	s_add_u32 m0, s8, 0x14000
	s_nop 0
	global_load_lds_dwordx4 v140, s[0:1]
	global_load_lds_dwordx4 v141, s[0:1] offset:1024
	global_load_lds_dwordx4 v142, s[0:1] offset:2048
	global_load_lds_dwordx4 v143, s[0:1] offset:3072
